# rmsnorm phase: next row x loads issued one row ahead into a second register set; forget bias loaded once per layer
# baseline (speedup 1.0000x reference)
; #define LAS __attribute__((address_space(3)))
; DI void norm_row(const float* xrow, const LAS f32x4* wfl, const float* fbias, bf16_t* orow, float* logf_b  , int s, int lane) {
;     ...
;     for (int j = 0; j < 8; ++j) { v[j] = ((const f32x4*)xrow)[lane + 64 * j]; ss += (v[j][0] * v[j][0] + v[j][1] * v[j][1]) + (v[j][2] * v[j][2] + v[j][3] * v[j][3]); }
; __global__ void __launch_bounds__(512, 2) mega_fwd(Args a) {
;     ...
;                 const f32x4* WFg = (const f32x4*)WSP(float, WS_WF) + (size_t)l * 4096;
;                 LAS f32x4* wfl = (LAS f32x4*)lds;
; #pragma unroll
;                 for (int i = 0; i < 8; ++i) wfl[tid + 512 * i] = WFg[tid + 512 * i];
;                 __syncthreads();
;             }
;             for (int rep = 0; rep < REP_N; ++rep)
;             for (int m = gw; m < MT; m += NGW) {
;                 const int b = m / S, s = m % S;
;                 norm_row(src + (size_t)m * DM, (const LAS f32x4*)lds, ap->fb + l * 8, XB + (size_t)m * DM, LOGF + (size_t)b * 8 * S, s, lane);
.LBB0_50:
	s_ashr_i32 s0, s16, 6
	v_readlane_b32 s1, v254, 2
	s_mov_b32 s85, s51
	s_add_i32 s0, s0, s1
	s_lshl_b64 s[10:11], s[84:85], 16
	s_waitcnt lgkmcnt(0)
	s_add_u32 s10, s4, s10
	s_addc_u32 s11, s5, s11
	v_ashrrev_i32_e32 v3, 31, v2
	v_lshl_add_u64 v[28:29], v[2:3], 4, s[10:11]
	v_add_co_u32_e32 v4, vcc, 0x24500000, v28
	v_lshl_add_u32 v0, v2, 4, 0
	s_nop 0
	v_addc_co_u32_e32 v5, vcc, 0, v29, vcc
	v_add_co_u32_e32 v8, vcc, 0x24502000, v28
	s_cmpk_lt_i32 s0, 0x4000
	s_nop 0
	v_addc_co_u32_e32 v9, vcc, 0, v29, vcc
	v_add_co_u32_e32 v12, vcc, 0x24504000, v28
	global_load_dwordx4 v[4:7], v[4:5], off
	s_nop 0
	global_load_dwordx4 v[8:11], v[8:9], off
	v_addc_co_u32_e32 v13, vcc, 0, v29, vcc
	v_add_co_u32_e32 v16, vcc, 0x24506000, v28
	s_nop 1
	v_addc_co_u32_e32 v17, vcc, 0, v29, vcc
	v_add_co_u32_e32 v20, vcc, 0x24508000, v28
	global_load_dwordx4 v[12:15], v[12:13], off
	s_nop 0
	global_load_dwordx4 v[16:19], v[16:17], off
	v_addc_co_u32_e32 v21, vcc, 0, v29, vcc
	v_add_co_u32_e32 v24, vcc, 0x2450a000, v28
	s_nop 1
	v_addc_co_u32_e32 v25, vcc, 0, v29, vcc
	v_add_co_u32_e32 v30, vcc, 0x2450c000, v28
	global_load_dwordx4 v[20:23], v[20:21], off
	s_nop 0
	global_load_dwordx4 v[24:27], v[24:25], off
	v_addc_co_u32_e32 v31, vcc, 0, v29, vcc
	v_add_co_u32_e32 v32, vcc, 0x2450e000, v28
	s_nop 1
	v_addc_co_u32_e32 v33, vcc, 0, v29, vcc
	global_load_dwordx4 v[28:31], v[30:31], off
	s_nop 0
	global_load_dwordx4 v[32:35], v[32:33], off
	s_waitcnt vmcnt(7)
	ds_write_b128 v0, v[4:7]
	s_waitcnt vmcnt(6)
	ds_write_b128 v0, v[8:11] offset:8192
	s_waitcnt vmcnt(5)
	ds_write_b128 v0, v[12:15] offset:16384
	s_waitcnt vmcnt(4)
	ds_write_b128 v0, v[16:19] offset:24576
	s_waitcnt vmcnt(3)
	ds_write_b128 v0, v[20:23] offset:32768
	s_waitcnt vmcnt(2)
	ds_write_b128 v0, v[24:27] offset:40960
	s_waitcnt vmcnt(1)
	ds_write_b128 v0, v[28:31] offset:49152
	s_waitcnt vmcnt(0)
	ds_write_b128 v0, v[32:35] offset:57344
	s_waitcnt lgkmcnt(0)
	s_barrier
	s_cbranch_scc0 .LBB0_55
	v_and_b32_e32 v4, 63, v2
	v_lshlrev_b32_e32 v0, 4, v4
	s_load_dwordx2 s[2:3], s[2:3], 0x28
	v_lshl_add_u64 v[42:43], s[8:9], 0, v[0:1]
	v_add_u32_e32 v50, 0, v0
	v_lshlrev_b32_e32 v0, 3, v4
	v_lshl_add_u64 v[2:3], s[4:5], 0, v[0:1]
	s_mov_b64 s[8:9], 0xa100000
	v_lshlrev_b32_e32 v0, 15, v4
	v_lshl_add_u64 v[44:45], v[2:3], 0, s[8:9]
	v_lshl_add_u64 v[2:3], s[4:5], 0, v[0:1]
	s_mov_b64 s[4:5], 0x24100000
	s_lshl_b32 s50, s84, 3
	v_lshl_add_u64 v[46:47], v[2:3], 0, s[4:5]
	s_lshl_b32 s24, s22, 3
	s_lshl_b64 s[4:5], s[50:51], 2
	s_waitcnt lgkmcnt(0)
	s_add_u32 s2, s2, s4
	s_addc_u32 s3, s3, s5
	v_lshlrev_b32_e32 v0, 2, v4
	v_cmp_gt_u32_e32 vcc, 8, v4
	v_cmp_eq_u32_e64 s[8:9], 7, v4
	v_cmp_eq_u32_e64 s[10:11], 6, v4
	v_cmp_eq_u32_e64 s[12:13], 5, v4
	v_cmp_eq_u32_e64 s[14:15], 4, v4
	v_cmp_eq_u32_e64 s[16:17], 3, v4
	v_cmp_eq_u32_e64 s[18:19], 2, v4
	v_cmp_eq_u32_e64 s[20:21], 1, v4
	v_lshl_add_u64 v[48:49], s[2:3], 0, v[0:1]
	s_and_saveexec_b64 s[22:23], vcc
	global_load_dword v232, v[48:49], off
	s_or_b64 exec, exec, s[22:23]
	s_ashr_i32 s1, s0, 31
	s_lshl_b64 s[2:3], s[0:1], 13
	v_lshl_add_u64 v[234:235], v[42:43], 0, s[2:3]
	s_mov_b64 s[22:23], 0x1000
	v_lshl_add_u64 v[236:237], v[234:235], 0, s[22:23]
	global_load_dwordx4 v[216:219], v[234:235], off
	global_load_dwordx4 v[212:215], v[234:235], off offset:2048
	global_load_dwordx4 v[208:211], v[236:237], off
	global_load_dwordx4 v[204:207], v[236:237], off offset:1024
	global_load_dwordx4 v[200:203], v[236:237], off offset:3072
	global_load_dwordx4 v[220:223], v[234:235], off offset:1024
	global_load_dwordx4 v[228:231], v[234:235], off offset:3072
	global_load_dwordx4 v[224:227], v[236:237], off offset:2048
	s_waitcnt vmcnt(0)
	s_branch .LBB0_53

; #define LAS __attribute__((address_space(3)))
; DI void norm_row(const float* xrow, const LAS f32x4* wfl, const float* fbias, bf16_t* orow, float* logf_b  , int s, int lane) {
;     ...
;     f32x4 v[8]; float ss = 0.f; float fl[8];
; #pragma unroll
;     for (int h = 0; h < 8; ++h) fl[h] = 0.f;
; #pragma unroll
;     for (int j = 0; j < 8; ++j) { v[j] = ((const f32x4*)xrow)[lane + 64 * j]; ss += (v[j][0] * v[j][0] + v[j][1] * v[j][1]) + (v[j][2] * v[j][2] + v[j][3] * v[j][3]); }
; #pragma unroll
;     for (int j = 0; j < 8; ++j) {
; #pragma unroll
;         for (int e = 0; e < 4; ++e) {
;             const float xg = v[j][e];
;             const f32x4 w0 = wfl[((j * 4 + e) * 2 + 0) * 64 + lane], w1 = wfl[((j * 4 + e) * 2 + 1) * 64 + lane];
;             fl[0] += xg * w0[0]; fl[1] += xg * w0[1]; fl[2] += xg * w0[2]; fl[3] += xg * w0[3];
;             fl[4] += xg * w1[0]; fl[5] += xg * w1[1]; fl[6] += xg * w1[2]; fl[7] += xg * w1[3];
; __global__ void __launch_bounds__(512, 2) mega_fwd(Args a) {
;     ...
;             for (int m = gw; m < MT; m += NGW) {
;                 const int b = m / S, s = m % S;
;                 norm_row(src + (size_t)m * DM, (const LAS f32x4*)lds, ap->fb + l * 8, XB + (size_t)m * DM, LOGF + (size_t)b * 8 * S, s, lane);
.LBB0_53:
	s_ashr_i32 s1, s0, 31
	s_lshl_b64 s[2:3], s[0:1], 13
	s_lshl_b64 s[2:3], s[0:1], 12
	s_nop 0
	ds_read_b128 v[58:61], v50
	ds_read_b128 v[62:65], v50 offset:1024
	ds_read_b128 v[66:69], v50 offset:2048
	ds_read_b128 v[70:73], v50 offset:3072
	ds_read_b128 v[38:41], v50 offset:4096
	ds_read_b128 v[34:37], v50 offset:5120
	ds_read_b128 v[74:77], v50 offset:6144
	ds_read_b128 v[78:81], v50 offset:7168
	ds_read_b128 v[82:85], v50 offset:8192
	ds_read_b128 v[86:89], v50 offset:9216
	ds_read_b128 v[90:93], v50 offset:10240
	ds_read_b128 v[94:97], v50 offset:11264
	s_nop 0
	s_waitcnt vmcnt(8)
	v_mov_b32_e32 v2, v200
	v_mov_b32_e32 v3, v201
	v_mov_b32_e32 v4, v202
	v_mov_b32_e32 v5, v203
	v_mov_b32_e32 v6, v204
	v_mov_b32_e32 v7, v205
	v_mov_b32_e32 v8, v206
	v_mov_b32_e32 v9, v207
	v_mov_b32_e32 v10, v208
	v_mov_b32_e32 v11, v209
	v_mov_b32_e32 v12, v210
	v_mov_b32_e32 v13, v211
	v_mov_b32_e32 v14, v212
	v_mov_b32_e32 v15, v213
	v_mov_b32_e32 v16, v214
	v_mov_b32_e32 v17, v215
	v_mov_b32_e32 v18, v216
	v_mov_b32_e32 v19, v217
	v_mov_b32_e32 v20, v218
	v_mov_b32_e32 v21, v219
	v_mov_b32_e32 v22, v220
	v_mov_b32_e32 v23, v221
	v_mov_b32_e32 v24, v222
	v_mov_b32_e32 v25, v223
	v_mov_b32_e32 v26, v224
	v_mov_b32_e32 v27, v225
	v_mov_b32_e32 v28, v226
	v_mov_b32_e32 v29, v227
	v_mov_b32_e32 v30, v228
	v_mov_b32_e32 v31, v229
	v_mov_b32_e32 v32, v230
	v_mov_b32_e32 v33, v231
	s_add_i32 s22, s0, s24
	s_cmpk_gt_i32 s22, 0x3fff
	s_cbranch_scc1 .Lnorm_nopf
	s_ashr_i32 s23, s22, 31
	s_lshl_b64 s[22:23], s[22:23], 13
	v_lshl_add_u64 v[234:235], v[42:43], 0, s[22:23]
	s_mov_b64 s[22:23], 0x1000
	v_lshl_add_u64 v[236:237], v[234:235], 0, s[22:23]
	global_load_dwordx4 v[216:219], v[234:235], off
	global_load_dwordx4 v[212:215], v[234:235], off offset:2048
	global_load_dwordx4 v[208:211], v[236:237], off
	global_load_dwordx4 v[204:207], v[236:237], off offset:1024
	global_load_dwordx4 v[200:203], v[236:237], off offset:3072
	global_load_dwordx4 v[220:223], v[234:235], off offset:1024
	global_load_dwordx4 v[228:231], v[234:235], off offset:3072
	global_load_dwordx4 v[224:227], v[236:237], off offset:2048
.Lnorm_nopf:
	s_waitcnt lgkmcnt(11)
	v_fma_f32 v57, v18, v58, 0
	v_fma_f32 v56, v18, v59, 0
	v_fma_f32 v55, v18, v60, 0
	v_fma_f32 v54, v18, v61, 0
	s_waitcnt lgkmcnt(10)
	v_fma_f32 v53, v18, v62, 0
	v_fma_f32 v52, v18, v63, 0
	v_fma_f32 v51, v18, v64, 0
	v_fma_f32 v0, v18, v65, 0
	v_pk_mul_f32 v[58:59], v[16:17], v[16:17]
	v_pk_mul_f32 v[98:99], v[14:15], v[14:15]
	s_waitcnt lgkmcnt(9)
	v_fmac_f32_e32 v57, v19, v66
	v_fmac_f32_e32 v56, v19, v67
	v_fmac_f32_e32 v55, v19, v68
	v_fmac_f32_e32 v54, v19, v69
	s_waitcnt lgkmcnt(8)
	v_fmac_f32_e32 v53, v19, v70
	v_fmac_f32_e32 v52, v19, v71
	v_fmac_f32_e32 v51, v19, v72
	v_fmac_f32_e32 v0, v19, v73
	v_pk_mov_b32 v[66:67], v[98:99], v[58:59] op_sel:[1,0]
	v_mov_b32_e32 v99, v59
	v_pk_mul_f32 v[68:69], v[8:9], v[8:9]
	v_pk_mul_f32 v[70:71], v[6:7], v[6:7]
	s_waitcnt lgkmcnt(7)
	v_fmac_f32_e32 v57, v20, v38
	v_fmac_f32_e32 v56, v20, v39
	v_fmac_f32_e32 v55, v20, v40
	v_fmac_f32_e32 v54, v20, v41
	s_waitcnt lgkmcnt(6)
	v_fmac_f32_e32 v53, v20, v34
	v_fmac_f32_e32 v52, v20, v35
	v_fmac_f32_e32 v51, v20, v36
	v_fmac_f32_e32 v0, v20, v37
	v_pk_add_f32 v[34:35], v[66:67], v[98:99]
	v_pk_mov_b32 v[36:37], v[70:71], v[68:69] op_sel:[1,0]
	v_mov_b32_e32 v71, v69
	ds_read_b128 v[38:41], v50 offset:12288
	ds_read_b128 v[66:69], v50 offset:13312
	s_waitcnt lgkmcnt(7)
	v_fmac_f32_e32 v57, v21, v74
	v_fmac_f32_e32 v56, v21, v75
	v_fmac_f32_e32 v55, v21, v76
	v_fmac_f32_e32 v54, v21, v77
	s_waitcnt lgkmcnt(6)
	v_fmac_f32_e32 v53, v21, v78
	v_fmac_f32_e32 v52, v21, v79
	v_fmac_f32_e32 v51, v21, v80
	v_fmac_f32_e32 v0, v21, v81
	s_waitcnt lgkmcnt(5)
	v_fmac_f32_e32 v57, v22, v82
	v_fmac_f32_e32 v56, v22, v83
	v_fmac_f32_e32 v55, v22, v84
	v_fmac_f32_e32 v54, v22, v85
	s_waitcnt lgkmcnt(4)
	v_fmac_f32_e32 v53, v22, v86
	v_fmac_f32_e32 v52, v22, v87
	v_fmac_f32_e32 v51, v22, v88
	v_fmac_f32_e32 v0, v22, v89
	s_waitcnt lgkmcnt(3)
	v_fmac_f32_e32 v57, v23, v90
	v_fmac_f32_e32 v56, v23, v91
	v_fmac_f32_e32 v55, v23, v92
	v_fmac_f32_e32 v54, v23, v93
	s_waitcnt lgkmcnt(2)
	v_fmac_f32_e32 v53, v23, v94
	v_fmac_f32_e32 v52, v23, v95
	v_fmac_f32_e32 v51, v23, v96
	v_fmac_f32_e32 v0, v23, v97
	s_waitcnt lgkmcnt(1)
	v_fmac_f32_e32 v57, v24, v38
	v_fmac_f32_e32 v56, v24, v39
	v_fmac_f32_e32 v55, v24, v40
	v_fmac_f32_e32 v54, v24, v41
	s_waitcnt lgkmcnt(0)
	v_fmac_f32_e32 v53, v24, v66
	ds_read_b128 v[38:41], v50 offset:14336
	v_fmac_f32_e32 v52, v24, v67
	v_fmac_f32_e32 v51, v24, v68
	v_fmac_f32_e32 v0, v24, v69
	ds_read_b128 v[66:69], v50 offset:15360
	s_waitcnt lgkmcnt(1)
	v_fmac_f32_e32 v57, v25, v38
	v_fmac_f32_e32 v56, v25, v39
	v_fmac_f32_e32 v55, v25, v40
	v_fmac_f32_e32 v54, v25, v41
	s_waitcnt lgkmcnt(0)
	v_fmac_f32_e32 v53, v25, v66
	ds_read_b128 v[38:41], v50 offset:16384
	v_fmac_f32_e32 v52, v25, v67
	v_fmac_f32_e32 v51, v25, v68
	v_fmac_f32_e32 v0, v25, v69
	ds_read_b128 v[66:69], v50 offset:17408
	s_waitcnt lgkmcnt(1)
	v_fmac_f32_e32 v57, v14, v38
	v_fmac_f32_e32 v56, v14, v39
	v_fmac_f32_e32 v55, v14, v40
	v_fmac_f32_e32 v54, v14, v41
	s_waitcnt lgkmcnt(0)
	v_fmac_f32_e32 v53, v14, v66
	ds_read_b128 v[38:41], v50 offset:18432
	v_fmac_f32_e32 v52, v14, v67
	v_fmac_f32_e32 v51, v14, v68
	v_fmac_f32_e32 v0, v14, v69
	ds_read_b128 v[66:69], v50 offset:19456
	s_waitcnt lgkmcnt(1)
	v_fmac_f32_e32 v57, v15, v38
	v_fmac_f32_e32 v56, v15, v39
	v_fmac_f32_e32 v55, v15, v40
	v_fmac_f32_e32 v54, v15, v41
	s_waitcnt lgkmcnt(0)
; DI void norm_row(const float* xrow, const LAS f32x4* wfl, const float* fbias, bf16_t* orow, float* logf_b  , int s, int lane) {
;     ...
;     for (int j = 0; j < 8; ++j) {
; #pragma unroll
;         for (int e = 0; e < 4; ++e) {
;             const float xg = v[j][e];
;             const f32x4 w0 = wfl[((j * 4 + e) * 2 + 0) * 64 + lane], w1 = wfl[((j * 4 + e) * 2 + 1) * 64 + lane];
;             fl[0] += xg * w0[0]; fl[1] += xg * w0[1]; fl[2] += xg * w0[2]; fl[3] += xg * w0[3];
;             fl[4] += xg * w1[0]; fl[5] += xg * w1[1]; fl[6] += xg * w1[2]; fl[7] += xg * w1[3];
;         }
	v_fmac_f32_e32 v53, v15, v66
	ds_read_b128 v[38:41], v50 offset:20480
	v_fmac_f32_e32 v52, v15, v67
	v_fmac_f32_e32 v51, v15, v68
	v_fmac_f32_e32 v0, v15, v69
	ds_read_b128 v[66:69], v50 offset:21504
	s_waitcnt lgkmcnt(1)
	v_fmac_f32_e32 v57, v16, v38
	v_fmac_f32_e32 v56, v16, v39
	v_fmac_f32_e32 v55, v16, v40
	v_fmac_f32_e32 v54, v16, v41
	s_waitcnt lgkmcnt(0)
	v_fmac_f32_e32 v53, v16, v66
	ds_read_b128 v[38:41], v50 offset:22528
	v_fmac_f32_e32 v52, v16, v67
	v_fmac_f32_e32 v51, v16, v68
	v_fmac_f32_e32 v0, v16, v69
	ds_read_b128 v[66:69], v50 offset:23552
	s_waitcnt lgkmcnt(1)
	v_fmac_f32_e32 v57, v17, v38
	v_fmac_f32_e32 v56, v17, v39
	v_fmac_f32_e32 v55, v17, v40
	v_fmac_f32_e32 v54, v17, v41
	s_waitcnt lgkmcnt(0)
	v_fmac_f32_e32 v53, v17, v66
	ds_read_b128 v[38:41], v50 offset:24576
	v_fmac_f32_e32 v52, v17, v67
	v_fmac_f32_e32 v51, v17, v68
	v_fmac_f32_e32 v0, v17, v69
	ds_read_b128 v[66:69], v50 offset:25600
	s_waitcnt lgkmcnt(1)
	v_fmac_f32_e32 v57, v30, v38
	v_fmac_f32_e32 v56, v30, v39
	v_fmac_f32_e32 v55, v30, v40
	v_fmac_f32_e32 v54, v30, v41
	s_waitcnt lgkmcnt(0)
	v_fmac_f32_e32 v53, v30, v66
	ds_read_b128 v[38:41], v50 offset:26624
	v_fmac_f32_e32 v52, v30, v67
	v_fmac_f32_e32 v51, v30, v68
	v_fmac_f32_e32 v0, v30, v69
	ds_read_b128 v[66:69], v50 offset:27648
	s_waitcnt lgkmcnt(1)
	v_fmac_f32_e32 v57, v31, v38
	v_fmac_f32_e32 v56, v31, v39
	v_fmac_f32_e32 v55, v31, v40
	v_fmac_f32_e32 v54, v31, v41
	s_waitcnt lgkmcnt(0)
	v_fmac_f32_e32 v53, v31, v66
	ds_read_b128 v[38:41], v50 offset:28672
	v_fmac_f32_e32 v52, v31, v67
	v_fmac_f32_e32 v51, v31, v68
	v_fmac_f32_e32 v0, v31, v69
	ds_read_b128 v[66:69], v50 offset:29696
	s_waitcnt lgkmcnt(1)
	v_fmac_f32_e32 v57, v32, v38
	v_fmac_f32_e32 v56, v32, v39
	v_fmac_f32_e32 v55, v32, v40
	v_fmac_f32_e32 v54, v32, v41
	s_waitcnt lgkmcnt(0)
	v_fmac_f32_e32 v53, v32, v66
	ds_read_b128 v[38:41], v50 offset:30720
	v_fmac_f32_e32 v52, v32, v67
	v_fmac_f32_e32 v51, v32, v68
	v_fmac_f32_e32 v0, v32, v69
	ds_read_b128 v[66:69], v50 offset:31744
	s_waitcnt lgkmcnt(1)
	v_fmac_f32_e32 v57, v33, v38
	v_fmac_f32_e32 v56, v33, v39
	v_fmac_f32_e32 v55, v33, v40
	v_fmac_f32_e32 v54, v33, v41
	s_waitcnt lgkmcnt(0)
	v_fmac_f32_e32 v53, v33, v66
	ds_read_b128 v[38:41], v50 offset:32768
	v_fmac_f32_e32 v52, v33, v67
	v_fmac_f32_e32 v51, v33, v68
	v_fmac_f32_e32 v0, v33, v69
	ds_read_b128 v[66:69], v50 offset:33792
	s_waitcnt lgkmcnt(1)
	v_fmac_f32_e32 v57, v10, v38
	v_fmac_f32_e32 v56, v10, v39
	v_fmac_f32_e32 v55, v10, v40
	v_fmac_f32_e32 v54, v10, v41
	s_waitcnt lgkmcnt(0)
	v_fmac_f32_e32 v53, v10, v66
	ds_read_b128 v[38:41], v50 offset:34816
	v_fmac_f32_e32 v52, v10, v67
	v_fmac_f32_e32 v51, v10, v68
	v_fmac_f32_e32 v0, v10, v69
	ds_read_b128 v[66:69], v50 offset:35840
	s_waitcnt lgkmcnt(1)
	v_fmac_f32_e32 v57, v11, v38
	v_fmac_f32_e32 v56, v11, v39
	v_fmac_f32_e32 v55, v11, v40
	v_fmac_f32_e32 v54, v11, v41
	s_waitcnt lgkmcnt(0)
	v_fmac_f32_e32 v53, v11, v66
	ds_read_b128 v[38:41], v50 offset:36864
	v_fmac_f32_e32 v52, v11, v67
	v_fmac_f32_e32 v51, v11, v68
	v_fmac_f32_e32 v0, v11, v69
	ds_read_b128 v[66:69], v50 offset:37888
	s_waitcnt lgkmcnt(1)
	v_fmac_f32_e32 v57, v12, v38
	v_fmac_f32_e32 v56, v12, v39
	v_fmac_f32_e32 v55, v12, v40
	v_fmac_f32_e32 v54, v12, v41
	s_waitcnt lgkmcnt(0)
	v_fmac_f32_e32 v53, v12, v66
	ds_read_b128 v[38:41], v50 offset:38912
	v_fmac_f32_e32 v52, v12, v67
	v_fmac_f32_e32 v51, v12, v68
	v_fmac_f32_e32 v0, v12, v69
	ds_read_b128 v[66:69], v50 offset:39936
	s_waitcnt lgkmcnt(1)
	v_fmac_f32_e32 v57, v13, v38
	v_fmac_f32_e32 v56, v13, v39
	v_fmac_f32_e32 v55, v13, v40
	v_fmac_f32_e32 v54, v13, v41
	s_waitcnt lgkmcnt(0)
	v_fmac_f32_e32 v53, v13, v66
	ds_read_b128 v[38:41], v50 offset:40960
	v_fmac_f32_e32 v52, v13, v67
	v_fmac_f32_e32 v51, v13, v68
	v_fmac_f32_e32 v0, v13, v69
	ds_read_b128 v[66:69], v50 offset:41984
	s_waitcnt lgkmcnt(1)
	v_fmac_f32_e32 v57, v6, v38
	v_fmac_f32_e32 v56, v6, v39
	v_fmac_f32_e32 v55, v6, v40
	v_fmac_f32_e32 v54, v6, v41
	s_waitcnt lgkmcnt(0)
	v_fmac_f32_e32 v53, v6, v66
	ds_read_b128 v[38:41], v50 offset:43008
	v_fmac_f32_e32 v52, v6, v67
	v_fmac_f32_e32 v51, v6, v68
	v_fmac_f32_e32 v0, v6, v69
	ds_read_b128 v[66:69], v50 offset:44032
	s_waitcnt lgkmcnt(1)
	v_fmac_f32_e32 v57, v7, v38
	v_fmac_f32_e32 v56, v7, v39
	v_fmac_f32_e32 v55, v7, v40
	v_fmac_f32_e32 v54, v7, v41
	s_waitcnt lgkmcnt(0)
	v_fmac_f32_e32 v53, v7, v66
	ds_read_b128 v[38:41], v50 offset:45056
	v_fmac_f32_e32 v52, v7, v67
	v_fmac_f32_e32 v51, v7, v68
	v_fmac_f32_e32 v0, v7, v69
	ds_read_b128 v[66:69], v50 offset:46080
	s_waitcnt lgkmcnt(1)
	v_fmac_f32_e32 v57, v8, v38
	v_fmac_f32_e32 v56, v8, v39
	v_fmac_f32_e32 v55, v8, v40
	v_fmac_f32_e32 v54, v8, v41
	s_waitcnt lgkmcnt(0)
	v_fmac_f32_e32 v53, v8, v66
	ds_read_b128 v[38:41], v50 offset:47104
	v_fmac_f32_e32 v52, v8, v67
	v_fmac_f32_e32 v51, v8, v68
	v_fmac_f32_e32 v0, v8, v69
	ds_read_b128 v[66:69], v50 offset:48128
	s_waitcnt lgkmcnt(1)
	v_fmac_f32_e32 v57, v9, v38
	v_fmac_f32_e32 v56, v9, v39
	v_fmac_f32_e32 v55, v9, v40
	v_fmac_f32_e32 v54, v9, v41
	s_waitcnt lgkmcnt(0)
	v_fmac_f32_e32 v53, v9, v66
	ds_read_b128 v[38:41], v50 offset:49152
	v_fmac_f32_e32 v52, v9, v67
	v_fmac_f32_e32 v51, v9, v68
	v_fmac_f32_e32 v0, v9, v69
	ds_read_b128 v[66:69], v50 offset:50176
	s_waitcnt lgkmcnt(1)
	v_fmac_f32_e32 v57, v26, v38
	v_fmac_f32_e32 v56, v26, v39
	v_fmac_f32_e32 v55, v26, v40
	v_fmac_f32_e32 v54, v26, v41
	s_waitcnt lgkmcnt(0)
	v_fmac_f32_e32 v53, v26, v66
	ds_read_b128 v[38:41], v50 offset:51200
	v_fmac_f32_e32 v52, v26, v67
	v_fmac_f32_e32 v51, v26, v68
	v_fmac_f32_e32 v0, v26, v69
	ds_read_b128 v[66:69], v50 offset:52224
	s_waitcnt lgkmcnt(1)
; DI float wave_sum(float v) { v += shx<1>(v); v += shx<2>(v); v += shx<4>(v); v += shx<8>(v); v += shx<16>(v); v += shx<32>(v); return v; }
; DI void norm_row(const float* xrow, const LAS f32x4* wfl, const float* fbias, bf16_t* orow, float* logf_b  , int s, int lane) {
;     ...
;     for (int j = 0; j < 8; ++j) { v[j] = ((const f32x4*)xrow)[lane + 64 * j]; ss += (v[j][0] * v[j][0] + v[j][1] * v[j][1]) + (v[j][2] * v[j][2] + v[j][3] * v[j][3]); }
; #pragma unroll
;     for (int j = 0; j < 8; ++j) {
; #pragma unroll
;         for (int e = 0; e < 4; ++e) {
;             const float xg = v[j][e];
;             const f32x4 w0 = wfl[((j * 4 + e) * 2 + 0) * 64 + lane], w1 = wfl[((j * 4 + e) * 2 + 1) * 64 + lane];
;             fl[0] += xg * w0[0]; fl[1] += xg * w0[1]; fl[2] += xg * w0[2]; fl[3] += xg * w0[3];
;             fl[4] += xg * w1[0]; fl[5] += xg * w1[1]; fl[6] += xg * w1[2]; fl[7] += xg * w1[3];
;         }
;     }
;     ss = wave_sum(ss);
; #pragma unroll
;     for (int h = 0; h < 8; ++h) fl[h] = wave_sum(fl[h]);
	v_fmac_f32_e32 v57, v27, v38
	v_fmac_f32_e32 v56, v27, v39
	v_fmac_f32_e32 v55, v27, v40
	v_fmac_f32_e32 v54, v27, v41
	s_waitcnt lgkmcnt(0)
	v_fmac_f32_e32 v53, v27, v66
	ds_read_b128 v[38:41], v50 offset:53248
	v_fmac_f32_e32 v52, v27, v67
	v_fmac_f32_e32 v51, v27, v68
	v_fmac_f32_e32 v0, v27, v69
	ds_read_b128 v[66:69], v50 offset:54272
	s_waitcnt lgkmcnt(1)
	v_fmac_f32_e32 v57, v28, v38
	v_fmac_f32_e32 v56, v28, v39
	v_fmac_f32_e32 v55, v28, v40
	v_fmac_f32_e32 v54, v28, v41
	s_waitcnt lgkmcnt(0)
	v_fmac_f32_e32 v53, v28, v66
	ds_read_b128 v[38:41], v50 offset:55296
	v_fmac_f32_e32 v52, v28, v67
	v_fmac_f32_e32 v51, v28, v68
	v_fmac_f32_e32 v0, v28, v69
	ds_read_b128 v[66:69], v50 offset:56320
	s_waitcnt lgkmcnt(1)
	v_fmac_f32_e32 v57, v29, v38
	v_fmac_f32_e32 v56, v29, v39
	v_fmac_f32_e32 v55, v29, v40
	v_fmac_f32_e32 v54, v29, v41
	s_waitcnt lgkmcnt(0)
	v_fmac_f32_e32 v53, v29, v66
	ds_read_b128 v[38:41], v50 offset:57344
	v_fmac_f32_e32 v52, v29, v67
	v_fmac_f32_e32 v51, v29, v68
	v_fmac_f32_e32 v0, v29, v69
	ds_read_b128 v[66:69], v50 offset:58368
	s_waitcnt lgkmcnt(1)
	v_fmac_f32_e32 v57, v2, v38
	v_fmac_f32_e32 v56, v2, v39
	v_fmac_f32_e32 v55, v2, v40
	v_fmac_f32_e32 v54, v2, v41
	s_waitcnt lgkmcnt(0)
	v_fmac_f32_e32 v53, v2, v66
	ds_read_b128 v[38:41], v50 offset:59392
	v_fmac_f32_e32 v52, v2, v67
	v_fmac_f32_e32 v51, v2, v68
	v_fmac_f32_e32 v0, v2, v69
	ds_read_b128 v[66:69], v50 offset:60416
	v_pk_add_f32 v[36:37], v[36:37], v[70:71]
	v_mov_b32_e32 v70, v21
	v_mov_b32_e32 v71, v25
	v_pk_mul_f32 v[70:71], v[70:71], v[70:71]
	s_waitcnt lgkmcnt(0)
	v_fmac_f32_e32 v53, v3, v66
	v_fmac_f32_e32 v52, v3, v67
	v_fmac_f32_e32 v51, v3, v68
	v_fmac_f32_e32 v0, v3, v69
	v_mov_b32_e32 v66, v19
	v_mov_b32_e32 v67, v23
	v_mov_b32_e32 v68, v20
	v_mov_b32_e32 v69, v24
	v_pk_mul_f32 v[66:67], v[66:67], v[66:67]
	v_pk_fma_f32 v[68:69], v[68:69], v[68:69], v[70:71]
	v_mov_b32_e32 v70, v18
	v_mov_b32_e32 v71, v22
	v_pk_fma_f32 v[66:67], v[70:71], v[70:71], v[66:67]
	v_fmac_f32_e32 v57, v3, v38
	v_fmac_f32_e32 v56, v3, v39
	v_fmac_f32_e32 v55, v3, v40
	v_fmac_f32_e32 v54, v3, v41
	ds_read_b128 v[38:41], v50 offset:61440
	v_pk_add_f32 v[70:71], v[66:67], v[68:69]
	v_mul_f32_e32 v66, v31, v31
	v_mul_f32_e32 v64, v12, v12
	v_pk_fma_f32 v[66:67], v[30:31], v[30:31], v[66:67] op_sel_hi:[1,1,0]
	v_mul_f32_e32 v65, v4, v4
	v_mov_b32_e32 v67, v64
	v_mul_f32_e32 v64, v33, v33
	v_mul_f32_e32 v62, v13, v13
	v_pk_fma_f32 v[68:69], v[32:33], v[32:33], v[64:65] op_sel_hi:[1,1,0]
	v_mul_f32_e32 v59, v10, v10
	v_mov_b32_e32 v69, v62
	v_mul_f32_e32 v58, v11, v11
	v_pk_add_f32 v[72:73], v[66:67], v[68:69]
	ds_read_b128 v[66:69], v50 offset:62464
	s_waitcnt lgkmcnt(1)
	v_fmac_f32_e32 v57, v4, v38
	v_fmac_f32_e32 v56, v4, v39
	v_pk_add_f32 v[38:39], v[70:71], v[70:71] op_sel:[0,1] op_sel_hi:[1,0]
	v_pk_add_f32 v[34:35], v[34:35], v[34:35] op_sel:[0,1] op_sel_hi:[1,0]
	v_mov_b32_e32 v39, v59
	v_mov_b32_e32 v35, v58
	v_pk_add_f32 v[34:35], v[38:39], v[34:35]
	v_fmac_f32_e32 v55, v4, v40
	v_pk_add_f32 v[34:35], v[34:35], v[72:73]
	v_mul_f32_e32 v38, v27, v27
	v_mul_f32_e32 v40, v29, v29
	v_mul_f32_e32 v61, v2, v2
	v_mul_f32_e32 v60, v3, v3
	v_mul_f32_e32 v63, v5, v5
	v_pk_fma_f32 v[38:39], v[26:27], v[26:27], v[38:39] op_sel_hi:[1,1,0]
	v_pk_fma_f32 v[58:59], v[28:29], v[28:29], v[40:41] op_sel_hi:[1,1,0]
	v_pk_add_f32 v[34:35], v[34:35], v[34:35] op_sel:[0,1] op_sel_hi:[1,0]
	v_pk_add_f32 v[36:37], v[36:37], v[36:37] op_sel:[0,1] op_sel_hi:[1,0]
	v_mov_b32_e32 v39, v65
	v_mov_b32_e32 v59, v63
	v_mov_b32_e32 v35, v61
	v_mov_b32_e32 v37, v60
	v_pk_add_f32 v[38:39], v[38:39], v[58:59]
	v_pk_add_f32 v[34:35], v[34:35], v[36:37]
	v_fmac_f32_e32 v54, v4, v41
	v_pk_add_f32 v[34:35], v[34:35], v[38:39]
	s_waitcnt lgkmcnt(0)
	v_fmac_f32_e32 v53, v4, v66
	v_add_f32_e32 v38, v34, v35
	ds_swizzle_b32 v39, v38 offset:swizzle(SWAP,1)
	ds_read_b128 v[34:37], v50 offset:63488
	v_fmac_f32_e32 v51, v4, v68
	v_fmac_f32_e32 v0, v4, v69
	v_fmac_f32_e32 v52, v4, v67
	s_waitcnt lgkmcnt(1)
	v_add_f32_e32 v58, v38, v39
	ds_swizzle_b32 v59, v58 offset:swizzle(SWAP,2)
	ds_read_b128 v[38:41], v50 offset:64512
	s_waitcnt lgkmcnt(2)
	v_fmac_f32_e32 v57, v5, v34
	v_fmac_f32_e32 v56, v5, v35
	ds_swizzle_b32 v35, v57 offset:swizzle(SWAP,1)
	s_waitcnt lgkmcnt(2)
	v_add_f32_e32 v34, v58, v59
	ds_swizzle_b32 v58, v34 offset:swizzle(SWAP,4)
	v_fmac_f32_e32 v55, v5, v36
	v_fmac_f32_e32 v54, v5, v37
	s_waitcnt lgkmcnt(1)
	v_add_f32_e32 v35, v57, v35
	ds_swizzle_b32 v37, v35 offset:swizzle(SWAP,2)
	s_waitcnt lgkmcnt(1)
	v_add_f32_e32 v34, v34, v58
	ds_swizzle_b32 v36, v34 offset:swizzle(SWAP,8)
	v_fmac_f32_e32 v53, v5, v38
	ds_swizzle_b32 v38, v56 offset:swizzle(SWAP,1)
	s_waitcnt lgkmcnt(2)
	v_add_f32_e32 v35, v35, v37
	ds_swizzle_b32 v37, v35 offset:swizzle(SWAP,4)
	s_waitcnt lgkmcnt(2)
	v_add_f32_e32 v34, v34, v36
	ds_swizzle_b32 v36, v34 offset:swizzle(SWAP,16)
	v_fmac_f32_e32 v51, v5, v40
	v_fmac_f32_e32 v0, v5, v41
	ds_swizzle_b32 v41, v55 offset:swizzle(SWAP,1)
	v_fmac_f32_e32 v52, v5, v39
	s_waitcnt lgkmcnt(1)
	v_add_f32_e32 v40, v34, v36
	v_add_f32_e32 v34, v35, v37
	v_add_f32_e32 v36, v56, v38
	ds_swizzle_b32 v35, v34 offset:swizzle(SWAP,8)
	ds_swizzle_b32 v37, v36 offset:swizzle(SWAP,2)
	v_mov_b32_e32 v38, v40
	v_mov_b32_e32 v39, v40
	s_nop 1
	v_permlane32_swap_b32_e32 v38, v39
	s_waitcnt lgkmcnt(1)
	v_add_f32_e32 v34, v34, v35
	s_waitcnt lgkmcnt(0)
	v_add_f32_e32 v36, v36, v37
	ds_swizzle_b32 v35, v34 offset:swizzle(SWAP,16)
	ds_swizzle_b32 v37, v36 offset:swizzle(SWAP,4)
	v_cndmask_b32_e64 v66, v38, v39, s[6:7]
	ds_swizzle_b32 v39, v54 offset:swizzle(SWAP,1)
	v_add_f32_e32 v40, v40, v66
	s_waitcnt lgkmcnt(2)
; DI unsigned pk2(float lo, float hi) { return f2bf(lo) | (f2bf(hi) << 16); }
; DI float wave_sum(float v) { v += shx<1>(v); v += shx<2>(v); v += shx<4>(v); v += shx<8>(v); v += shx<16>(v); v += shx<32>(v); return v; }
; DI void norm_row(const float* xrow, const LAS f32x4* wfl, const float* fbias, bf16_t* orow, float* logf_b  , int s, int lane) {
;     ...
;     ss = wave_sum(ss);
; #pragma unroll
;     for (int h = 0; h < 8; ++h) fl[h] = wave_sum(fl[h]);
;     const float rstd = rsqrtf(ss * (1.0f / DM) + 1e-6f);
;     unsigned long long* o8 = (unsigned long long*)orow + lane;
; #pragma unroll
;     for (int j = 0; j < 8; ++j) o8[64 * j] = (unsigned long long)pk2(v[j][0] * rstd, v[j][1] * rstd) | ((unsigned long long)pk2(v[j][2] * rstd, v[j][3] * rstd) << 32);
	v_add_f32_e32 v34, v34, v35
	s_waitcnt lgkmcnt(1)
	v_add_f32_e32 v35, v36, v37
	v_add_f32_e32 v37, v55, v41
	ds_swizzle_b32 v36, v35 offset:swizzle(SWAP,8)
	ds_swizzle_b32 v38, v37 offset:swizzle(SWAP,2)
	v_fmamk_f32 v40, v40, 0x3a000000, v181
	v_mul_f32_e32 v66, 0x4b800000, v40
	v_cmp_gt_f32_e64 s[22:23], s77, v40
	s_waitcnt lgkmcnt(1)
	v_add_f32_e32 v35, v35, v36
	s_waitcnt lgkmcnt(0)
	v_add_f32_e32 v37, v37, v38
	ds_swizzle_b32 v36, v35 offset:swizzle(SWAP,16)
	ds_swizzle_b32 v38, v37 offset:swizzle(SWAP,4)
	v_cndmask_b32_e64 v40, v40, v66, s[22:23]
	v_rsq_f32_e32 v40, v40
	v_lshl_add_u64 v[68:69], v[44:45], 0, s[2:3]
	s_waitcnt lgkmcnt(1)
	v_add_f32_e32 v35, v35, v36
	s_waitcnt lgkmcnt(0)
	v_add_f32_e32 v36, v37, v38
	ds_swizzle_b32 v37, v36 offset:swizzle(SWAP,8)
	v_add_f32_e32 v38, v54, v39
	ds_swizzle_b32 v39, v38 offset:swizzle(SWAP,2)
	v_mul_f32_e32 v67, 0x45800000, v40
	v_cndmask_b32_e64 v40, v40, v67, s[22:23]
	s_waitcnt lgkmcnt(1)
	v_add_f32_e32 v36, v36, v37
	v_mul_f32_e32 v18, v18, v40
	ds_swizzle_b32 v37, v36 offset:swizzle(SWAP,16)
	s_waitcnt lgkmcnt(1)
	v_add_f32_e32 v38, v38, v39
	ds_swizzle_b32 v39, v53 offset:swizzle(SWAP,1)
	v_mul_f32_e32 v19, v19, v40
	v_bfe_u32 v67, v18, 16, 1
	v_add3_u32 v18, v18, v67, s78
	v_bfe_u32 v67, v19, 16, 1
	v_lshrrev_b32_e32 v18, 16, v18
	v_add3_u32 v19, v19, v67, s78
	v_and_or_b32 v18, v19, s76, v18
	v_mul_f32_e32 v19, v20, v40
	v_mul_f32_e32 v20, v21, v40
	v_bfe_u32 v21, v19, 16, 1
	s_waitcnt lgkmcnt(1)
	v_add_f32_e32 v36, v36, v37
	s_waitcnt lgkmcnt(0)
	v_add_f32_e32 v37, v53, v39
	v_add3_u32 v19, v19, v21, s78
	v_bfe_u32 v21, v20, 16, 1
	ds_swizzle_b32 v39, v37 offset:swizzle(SWAP,2)
	v_lshrrev_b32_e32 v19, 16, v19
	v_add3_u32 v20, v20, v21, s78
	ds_swizzle_b32 v41, v38 offset:swizzle(SWAP,4)
	v_and_or_b32 v19, v20, s76, v19
	global_store_dwordx2 v[68:69], v[18:19], off
	v_mul_f32_e32 v18, v22, v40
	v_mul_f32_e32 v19, v23, v40
	v_bfe_u32 v20, v18, 16, 1
	v_add3_u32 v18, v18, v20, s78
	v_bfe_u32 v20, v19, 16, 1
	s_waitcnt lgkmcnt(1)
	v_add_f32_e32 v37, v37, v39
	v_lshrrev_b32_e32 v18, 16, v18
	v_add3_u32 v19, v19, v20, s78
	s_waitcnt lgkmcnt(0)
	v_add_f32_e32 v38, v38, v41
	ds_swizzle_b32 v39, v37 offset:swizzle(SWAP,4)
	v_and_or_b32 v18, v19, s76, v18
	v_mul_f32_e32 v19, v24, v40
	ds_swizzle_b32 v41, v38 offset:swizzle(SWAP,8)
	v_mul_f32_e32 v20, v25, v40
	v_bfe_u32 v21, v19, 16, 1
	v_add3_u32 v19, v19, v21, s78
	v_bfe_u32 v21, v20, 16, 1
	v_lshrrev_b32_e32 v19, 16, v19
	v_add3_u32 v20, v20, v21, s78
	v_and_or_b32 v19, v20, s76, v19
	v_mul_f32_e32 v14, v14, v40
	s_waitcnt lgkmcnt(1)
	v_add_f32_e32 v39, v37, v39
	global_store_dwordx2 v[68:69], v[18:19], off offset:512
	v_mul_f32_e32 v15, v15, v40
	v_bfe_u32 v18, v14, 16, 1
	s_waitcnt lgkmcnt(0)
	v_add_f32_e32 v38, v38, v41
	ds_swizzle_b32 v61, v39 offset:swizzle(SWAP,8)
	v_add3_u32 v14, v14, v18, s78
	v_bfe_u32 v18, v15, 16, 1
	ds_swizzle_b32 v41, v38 offset:swizzle(SWAP,16)
	v_lshrrev_b32_e32 v14, 16, v14
	v_add3_u32 v15, v15, v18, s78
	v_and_or_b32 v14, v15, s76, v14
	v_mul_f32_e32 v15, v16, v40
	v_mul_f32_e32 v16, v17, v40
	v_bfe_u32 v17, v15, 16, 1
	v_add3_u32 v15, v15, v17, s78
	v_bfe_u32 v17, v16, 16, 1
	s_waitcnt lgkmcnt(1)
	v_add_f32_e32 v39, v39, v61
	v_lshrrev_b32_e32 v15, 16, v15
	v_add3_u32 v16, v16, v17, s78
	s_waitcnt lgkmcnt(0)
	v_add_f32_e32 v37, v38, v41
	ds_swizzle_b32 v38, v52 offset:swizzle(SWAP,1)
	ds_swizzle_b32 v41, v39 offset:swizzle(SWAP,16)
	v_and_or_b32 v15, v16, s76, v15
	global_store_dwordx2 v[68:69], v[14:15], off offset:1024
	v_mul_f32_e32 v14, v30, v40
	v_mul_f32_e32 v15, v31, v40
	v_bfe_u32 v16, v14, 16, 1
	v_add3_u32 v14, v14, v16, s78
	v_bfe_u32 v16, v15, 16, 1
	v_lshrrev_b32_e32 v14, 16, v14
	v_add3_u32 v15, v15, v16, s78
	s_waitcnt lgkmcnt(1)
	v_add_f32_e32 v62, v52, v38
	s_waitcnt lgkmcnt(0)
	v_add_f32_e32 v38, v39, v41
	ds_swizzle_b32 v39, v51 offset:swizzle(SWAP,1)
	v_and_or_b32 v14, v15, s76, v14
	v_mul_f32_e32 v15, v32, v40
	ds_swizzle_b32 v63, v62 offset:swizzle(SWAP,2)
	v_mul_f32_e32 v16, v33, v40
	v_bfe_u32 v17, v15, 16, 1
	v_add3_u32 v15, v15, v17, s78
	v_bfe_u32 v17, v16, 16, 1
	v_lshrrev_b32_e32 v15, 16, v15
	v_add3_u32 v16, v16, v17, s78
	v_and_or_b32 v15, v16, s76, v15
	v_mul_f32_e32 v10, v10, v40
	s_waitcnt lgkmcnt(1)
	v_add_f32_e32 v39, v51, v39
	global_store_dwordx2 v[68:69], v[14:15], off offset:1536
	v_mul_f32_e32 v11, v11, v40
	v_bfe_u32 v14, v10, 16, 1
	s_waitcnt lgkmcnt(0)
	v_add_f32_e32 v41, v62, v63
	ds_swizzle_b32 v51, v39 offset:swizzle(SWAP,2)
	ds_swizzle_b32 v63, v0 offset:swizzle(SWAP,1)
	v_add3_u32 v10, v10, v14, s78
	v_bfe_u32 v14, v11, 16, 1
	ds_swizzle_b32 v62, v41 offset:swizzle(SWAP,4)
	v_lshrrev_b32_e32 v10, 16, v10
	v_add3_u32 v11, v11, v14, s78
	v_and_or_b32 v10, v11, s76, v10
	v_mul_f32_e32 v11, v12, v40
	v_mul_f32_e32 v12, v13, v40
	v_bfe_u32 v13, v11, 16, 1
	v_add3_u32 v11, v11, v13, s78
	v_bfe_u32 v13, v12, 16, 1
	s_waitcnt lgkmcnt(2)
	v_add_f32_e32 v39, v39, v51
	s_waitcnt lgkmcnt(1)
	v_add_f32_e32 v0, v0, v63
	v_lshrrev_b32_e32 v11, 16, v11
	v_add3_u32 v12, v12, v13, s78
	s_waitcnt lgkmcnt(0)
	v_add_f32_e32 v41, v41, v62
	ds_swizzle_b32 v51, v39 offset:swizzle(SWAP,4)
	ds_swizzle_b32 v63, v0 offset:swizzle(SWAP,2)
	v_and_or_b32 v11, v12, s76, v11
	v_mul_f32_e32 v6, v6, v40
	ds_swizzle_b32 v62, v41 offset:swizzle(SWAP,8)
	global_store_dwordx2 v[68:69], v[10:11], off offset:2048
	v_mul_f32_e32 v7, v7, v40
	v_bfe_u32 v10, v6, 16, 1
	v_add3_u32 v6, v6, v10, s78
	v_bfe_u32 v10, v7, 16, 1
	v_lshrrev_b32_e32 v6, 16, v6
	v_add3_u32 v7, v7, v10, s78
	v_and_or_b32 v6, v7, s76, v6
	v_mul_f32_e32 v7, v8, v40
	s_waitcnt lgkmcnt(2)
	v_add_f32_e32 v39, v39, v51
	s_waitcnt lgkmcnt(1)
; DI unsigned pk2(float lo, float hi) { return f2bf(lo) | (f2bf(hi) << 16); }
; DI float wave_sum(float v) { v += shx<1>(v); v += shx<2>(v); v += shx<4>(v); v += shx<8>(v); v += shx<16>(v); v += shx<32>(v); return v; }
; DI void norm_row(const float* xrow, const LAS f32x4* wfl, const float* fbias, bf16_t* orow, float* logf_b  , int s, int lane) {
;     ...
;     for (int h = 0; h < 8; ++h) fl[h] = wave_sum(fl[h]);
;     const float rstd = rsqrtf(ss * (1.0f / DM) + 1e-6f);
;     unsigned long long* o8 = (unsigned long long*)orow + lane;
; #pragma unroll
;     for (int j = 0; j < 8; ++j) o8[64 * j] = (unsigned long long)pk2(v[j][0] * rstd, v[j][1] * rstd) | ((unsigned long long)pk2(v[j][2] * rstd, v[j][3] * rstd) << 32);
;     float mine = fl[0];
; #pragma unroll
;     for (int h = 1; h < 8; ++h) mine = (lane == h) ? fl[h] : mine;
;     if (lane < 8) {
	v_add_f32_e32 v63, v0, v63
	v_mul_f32_e32 v8, v9, v40
	v_bfe_u32 v9, v7, 16, 1
	s_waitcnt lgkmcnt(0)
	v_add_f32_e32 v41, v41, v62
	ds_swizzle_b32 v64, v39 offset:swizzle(SWAP,8)
	ds_swizzle_b32 v65, v63 offset:swizzle(SWAP,4)
	v_add3_u32 v7, v7, v9, s78
	v_bfe_u32 v9, v8, 16, 1
	ds_swizzle_b32 v62, v41 offset:swizzle(SWAP,16)
	v_lshrrev_b32_e32 v7, 16, v7
	v_add3_u32 v8, v8, v9, s78
	v_and_or_b32 v7, v8, s76, v7
	global_store_dwordx2 v[68:69], v[6:7], off offset:2560
	v_mul_f32_e32 v6, v26, v40
	v_mul_f32_e32 v7, v27, v40
	v_bfe_u32 v8, v6, 16, 1
	s_waitcnt lgkmcnt(2)
	v_add_f32_e32 v39, v39, v64
	s_waitcnt lgkmcnt(1)
	v_add_f32_e32 v63, v63, v65
	v_add3_u32 v6, v6, v8, s78
	v_bfe_u32 v8, v7, 16, 1
	s_waitcnt lgkmcnt(0)
	v_add_f32_e32 v0, v41, v62
	ds_swizzle_b32 v41, v39 offset:swizzle(SWAP,16)
	ds_swizzle_b32 v64, v63 offset:swizzle(SWAP,8)
	v_lshrrev_b32_e32 v6, 16, v6
	v_add3_u32 v7, v7, v8, s78
	v_and_or_b32 v6, v7, s76, v6
	v_mul_f32_e32 v7, v28, v40
	v_mul_f32_e32 v8, v29, v40
	v_bfe_u32 v9, v7, 16, 1
	v_add3_u32 v7, v7, v9, s78
	v_bfe_u32 v9, v8, 16, 1
	v_lshrrev_b32_e32 v7, 16, v7
	v_add3_u32 v8, v8, v9, s78
	s_waitcnt lgkmcnt(1)
	v_add_f32_e32 v39, v39, v41
	s_waitcnt lgkmcnt(0)
	v_add_f32_e32 v41, v63, v64
	v_and_or_b32 v7, v8, s76, v7
	v_mul_f32_e32 v2, v2, v40
	ds_swizzle_b32 v65, v41 offset:swizzle(SWAP,16)
	global_store_dwordx2 v[68:69], v[6:7], off offset:3072
	v_mul_f32_e32 v3, v3, v40
	v_bfe_u32 v6, v2, 16, 1
	v_add3_u32 v2, v2, v6, s78
	v_bfe_u32 v6, v3, 16, 1
	v_lshrrev_b32_e32 v2, 16, v2
	v_add3_u32 v3, v3, v6, s78
	v_and_or_b32 v2, v3, s76, v2
	v_mul_f32_e32 v3, v4, v40
	v_mul_f32_e32 v4, v5, v40
	v_bfe_u32 v5, v3, 16, 1
	s_waitcnt lgkmcnt(0)
	v_add_f32_e32 v41, v41, v65
	v_add3_u32 v3, v3, v5, s78
	v_bfe_u32 v5, v4, 16, 1
	v_mov_b32_e32 v55, v34
	v_mov_b32_e32 v56, v34
	v_mov_b32_e32 v54, v35
	v_mov_b32_e32 v57, v35
	v_mov_b32_e32 v53, v36
	v_mov_b32_e32 v58, v36
	v_mov_b32_e32 v59, v37
	v_mov_b32_e32 v60, v37
	v_mov_b32_e32 v52, v38
	v_mov_b32_e32 v61, v38
	v_mov_b32_e32 v51, v0
	v_mov_b32_e32 v62, v0
	v_mov_b32_e32 v63, v39
	v_mov_b32_e32 v64, v39
	v_mov_b32_e32 v65, v41
	v_mov_b32_e32 v66, v41
	v_lshrrev_b32_e32 v3, 16, v3
	v_add3_u32 v4, v4, v5, s78
	v_permlane32_swap_b32_e32 v55, v56
	v_permlane32_swap_b32_e32 v54, v57
	v_permlane32_swap_b32_e32 v53, v58
	v_permlane32_swap_b32_e32 v59, v60
	v_permlane32_swap_b32_e32 v52, v61
	v_permlane32_swap_b32_e32 v51, v62
	v_permlane32_swap_b32_e32 v63, v64
	v_permlane32_swap_b32_e32 v65, v66
	v_and_or_b32 v3, v4, s76, v3
	global_store_dwordx2 v[68:69], v[2:3], off offset:3584
	s_and_saveexec_b64 s[2:3], vcc
	s_cbranch_execz .LBB0_52
; DI void norm_row(const float* xrow, const LAS f32x4* wfl, const float* fbias, bf16_t* orow, float* logf_b  , int s, int lane) {
;     ...
;     float mine = fl[0];
; #pragma unroll
;     for (int h = 1; h < 8; ++h) mine = (lane == h) ? fl[h] : mine;
;     if (lane < 8) {
;         const float z = mine * rstd + fbias[lane];
;         const float lf = fminf(z, 0.f) - log1pf(expf(-fabsf(z)));
;         logf_b[(size_t)lane * S + s] = lf;
;     }
	v_mov_b32_e32 v4, v232
	v_cndmask_b32_e64 v5, v51, v62, s[6:7]
	v_cndmask_b32_e64 v6, v52, v61, s[6:7]
	v_cndmask_b32_e64 v7, v59, v60, s[6:7]
	v_cndmask_b32_e64 v8, v53, v58, s[6:7]
	v_cndmask_b32_e64 v9, v54, v57, s[6:7]
	v_cndmask_b32_e64 v10, v55, v56, s[6:7]
	v_add_f32_e32 v0, v0, v5
	v_add_f32_e32 v5, v38, v6
	v_add_f32_e32 v6, v37, v7
	v_add_f32_e32 v7, v36, v8
	v_add_f32_e32 v8, v35, v9
	v_add_f32_e32 v9, v34, v10
	v_cndmask_b32_e64 v8, v9, v8, s[20:21]
	v_cndmask_b32_e64 v7, v8, v7, s[18:19]
	v_cndmask_b32_e64 v6, v7, v6, s[16:17]
	v_cndmask_b32_e64 v3, v63, v64, s[6:7]
	v_cndmask_b32_e64 v5, v6, v5, s[14:15]
	v_cndmask_b32_e64 v2, v65, v66, s[6:7]
	v_add_f32_e32 v3, v39, v3
	v_cndmask_b32_e64 v0, v5, v0, s[12:13]
	v_add_f32_e32 v2, v41, v2
	v_cndmask_b32_e64 v0, v0, v3, s[10:11]
	v_cndmask_b32_e64 v0, v0, v2, s[8:9]
	s_mov_b32 s5, 0xb2a5705f
	s_lshr_b32 s1, s1, 19
	s_add_i32 s1, s0, s1
	s_ashr_i32 s22, s1, 13
	s_ashr_i32 s23, s22, 31
	s_mov_b32 s25, 0x42ce8ed0
	s_lshl_b64 s[22:23], s[22:23], 18
	s_mov_b32 s26, 0xc2b17218
	s_mov_b32 s27, 0x3f2aaaab
	v_mov_b32_e32 v12, 0x3ecc95a3
	s_and_b32 s1, s1, 0xffffe000
	s_sub_i32 s4, s0, s1
	s_mov_b32 s1, 0x7f800000
	v_fmac_f32_e32 v4, v40, v0
	v_mul_f32_e64 v0, |v4|, s99
	v_fma_f32 v2, |v4|, s99, -v0
	v_rndne_f32_e32 v3, v0
	v_fma_f32 v2, |v4|, s5, v2
	v_sub_f32_e32 v0, v0, v3
	v_add_f32_e32 v0, v0, v2
	v_cvt_i32_f32_e32 v5, v3
	v_exp_f32_e32 v0, v0
	v_lshl_add_u64 v[2:3], v[46:47], 0, s[22:23]
	v_cmp_ngt_f32_e64 s[22:23], |v4|, s25
	v_min_f32_e32 v18, 0, v4
	v_ldexp_f32 v0, v0, v5
	v_cndmask_b32_e64 v0, 0, v0, s[22:23]
	v_cmp_nlt_f32_e64 s[22:23], |v4|, s26
	s_ashr_i32 s5, s4, 31
	v_lshl_add_u64 v[2:3], s[4:5], 2, v[2:3]
	v_cndmask_b32_e64 v0, v191, v0, s[22:23]
	v_add_f32_e32 v6, 1.0, v0
	v_add_f32_e32 v7, -1.0, v6
	v_frexp_mant_f32_e32 v8, v6
	v_cvt_f64_f32_e32 v[4:5], v6
	v_sub_f32_e32 v9, v7, v6
	v_frexp_exp_i32_f64_e32 v4, v[4:5]
	v_cmp_gt_f32_e64 s[22:23], s27, v8
	v_sub_f32_e32 v7, v0, v7
	v_add_f32_e32 v5, 1.0, v9
	v_subbrev_co_u32_e64 v4, s[22:23], 0, v4, s[22:23]
	v_add_f32_e32 v5, v7, v5
	v_sub_u32_e32 v7, 0, v4
	v_ldexp_f32 v6, v6, v7
	v_add_f32_e32 v8, -1.0, v6
	v_add_f32_e32 v9, 1.0, v6
	v_ldexp_f32 v5, v5, v7
	v_add_f32_e32 v7, 1.0, v8
	v_add_f32_e32 v10, -1.0, v9
	v_sub_f32_e32 v7, v6, v7
	v_sub_f32_e32 v6, v6, v10
	v_add_f32_e32 v10, v5, v7
	v_add_f32_e32 v5, v5, v6
	v_add_f32_e32 v13, v9, v5
	v_rcp_f32_e32 v14, v13
	v_add_f32_e32 v7, v8, v10
	v_sub_f32_e32 v8, v8, v7
	v_sub_f32_e32 v6, v9, v13
	v_mul_f32_e32 v16, v7, v14
	v_add_f32_e32 v15, v10, v8
	v_mul_f32_e32 v8, v13, v16
	v_add_f32_e32 v5, v5, v6
	v_fma_f32 v10, v16, v13, -v8
	v_fmac_f32_e32 v10, v16, v5
	v_add_f32_e32 v6, v8, v10
	v_sub_f32_e32 v9, v7, v6
	v_mov_b32_e32 v11, v6
	v_pk_add_f32 v[6:7], v[6:7], v[8:9] neg_lo:[0,1] neg_hi:[0,1]
	v_cvt_f32_i32_e32 v4, v4
	v_pk_add_f32 v[6:7], v[6:7], v[10:11] neg_lo:[0,1] neg_hi:[0,1]
	v_cmp_neq_f32_e64 s[22:23], s1, v0
	v_add_f32_e32 v7, v15, v7
	v_add_f32_e32 v6, v6, v7
	v_add_f32_e32 v7, v9, v6
	v_mul_f32_e32 v11, v14, v7
	v_mul_f32_e32 v8, v13, v11
	v_sub_f32_e32 v9, v9, v7
	v_add_f32_e32 v17, v16, v11
	v_fma_f32 v10, v11, v13, -v8
	v_add_f32_e32 v15, v6, v9
	v_sub_f32_e32 v6, v17, v16
	v_fmac_f32_e32 v10, v11, v5
	v_sub_f32_e32 v5, v11, v6
	v_add_f32_e32 v6, v8, v10
	v_sub_f32_e32 v9, v7, v6
	v_mov_b32_e32 v11, v6
	v_pk_add_f32 v[6:7], v[6:7], v[8:9] neg_lo:[0,1] neg_hi:[0,1]
	s_mov_b32 s1, 0x33800000
	v_pk_add_f32 v[6:7], v[6:7], v[10:11] neg_lo:[0,1] neg_hi:[0,1]
	s_nop 0
	v_add_f32_e32 v7, v15, v7
	v_add_f32_e32 v6, v6, v7
	v_add_f32_e32 v6, v9, v6
	v_mul_f32_e32 v6, v14, v6
	v_add_f32_e32 v5, v5, v6
	v_add_f32_e32 v6, v17, v5
	v_mul_f32_e32 v8, v6, v6
	v_sub_f32_e32 v9, v6, v17
	v_fmamk_f32 v10, v8, 0x3e9b6dac, v12
	v_sub_f32_e32 v9, v5, v9
	v_mul_f32_e32 v5, v6, v8
	v_fmaak_f32 v165, v8, v10, 0x3f2aaada
	v_ldexp_f32 v11, v9, 1
	v_pk_mul_f32 v[8:9], v[4:5], v[164:165]
	v_ldexp_f32 v7, v6, 1
	v_fma_f32 v6, v4, s96, -v8
	v_fmac_f32_e32 v6, 0xb102e308, v4
	v_pk_add_f32 v[4:5], v[8:9], v[6:7]
	v_mov_b32_e32 v10, v8
	v_sub_f32_e32 v14, v5, v7
	v_pk_add_f32 v[12:13], v[4:5], v[8:9] neg_lo:[0,1] neg_hi:[0,1]
	v_sub_f32_e32 v8, v9, v14
	v_add_f32_e32 v11, v11, v8
	v_pk_add_f32 v[8:9], v[4:5], v[10:11]
	v_mov_b32_e32 v7, v4
	v_mov_b32_e32 v13, v9
	v_pk_add_f32 v[16:17], v[6:7], v[12:13] neg_lo:[0,1] neg_hi:[0,1]
	v_pk_add_f32 v[6:7], v[6:7], v[12:13]
	v_mov_b32_e32 v15, v4
	v_pk_add_f32 v[12:13], v[6:7], v[4:5] op_sel:[1,0] op_sel_hi:[0,1] neg_lo:[0,1] neg_hi:[0,1]
	v_mov_b32_e32 v14, v11
	v_mov_b32_e32 v10, v9
	v_mov_b32_e32 v11, v7
	v_pk_mov_b32 v[4:5], v[4:5], v[12:13] op_sel:[1,0]
	v_pk_add_f32 v[8:9], v[8:9], v[12:13] op_sel_hi:[1,0] neg_lo:[0,1] neg_hi:[0,1]
	v_pk_add_f32 v[4:5], v[10:11], v[4:5] neg_lo:[0,1] neg_hi:[0,1]
	v_mov_b32_e32 v8, v16
	v_pk_add_f32 v[4:5], v[14:15], v[4:5] neg_lo:[0,1] neg_hi:[0,1]
	v_mov_b32_e32 v17, v7
	v_pk_add_f32 v[8:9], v[8:9], v[4:5]
	s_nop 0
	v_pk_add_f32 v[10:11], v[8:9], v[8:9] op_sel:[0,1] op_sel_hi:[1,0]
	s_nop 0
	v_pk_add_f32 v[6:7], v[6:7], v[10:11] op_sel:[1,0] op_sel_hi:[0,1]
	v_mov_b32_e32 v9, v6
	v_mov_b32_e32 v5, v10
	v_pk_add_f32 v[10:11], v[8:9], v[16:17] neg_lo:[0,1] neg_hi:[0,1]
	s_nop 0
	v_sub_f32_e32 v7, v8, v10
	v_pk_add_f32 v[4:5], v[4:5], v[10:11] neg_lo:[0,1] neg_hi:[0,1]
	v_sub_f32_e32 v7, v16, v7
	v_add_f32_e32 v4, v4, v7
	v_add_f32_e32 v4, v4, v5
	v_add_f32_e32 v4, v6, v4
	v_cndmask_b32_e64 v4, v191, v4, s[22:23]
	v_cmp_lt_f32_e64 s[22:23], |v0|, s1
	s_nop 1
	v_cndmask_b32_e64 v0, v4, v0, s[22:23]
	v_sub_f32_e32 v0, v18, v0
	global_store_dword v[2:3], v0, off
	s_branch .LBB0_52
